# P2 queue order: LRU levels pulled forward (two levels per group of 256 entries)
# baseline (speedup 1.0000x reference)
; #define LAS __attribute__((address_space(3)))
; __device__ __forceinline__ void lru_unit(const Ctx& C, const Params& p, int l, int unit) {
;     const int tc = unit >> 6, b = (unit >> 3) & 7, nb = unit & 7, c0 = nb * 64;
;     const bf16* Zb = (const bf16*)(C.ws + WS_Z) + (size_t)b * SEQ * ZC;
;     bf16* Ob = (bf16*)(C.ws + WS_O) + (size_t)b * SEQ * OC;
;     float* carr = (float*)(C.ws + WS_LC) + (size_t)(l * 1024) * 64;
;     unsigned* flg = (unsigned*)(C.ws + WS_LF) + (size_t)(l * 1024) * 16;
;     LAS unsigned char* XCB = C.lds;
;     LAS float* RF = (LAS float*)(C.lds + 18432);
;     LAS float* IF = (LAS float*)(C.lds + 18432 + 32768);
;     LAS float* AGG = (LAS float*)(C.lds + 83968);
;     LAS float* CAR = (LAS float*)(C.lds + 88064);
;     LAS float* CARP = (LAS float*)(C.lds + 88320);
;     LAS float* CIN = (LAS float*)(C.lds + 88576);
;     LAS bf16* HL = (LAS bf16*)(C.lds + 90112);
;     LAS bf16* PGL = (LAS bf16*)(C.lds + 122880);
;     const int tid = C.tid, lane = C.lane, i16 = lane & 15, g = lane >> 4, c = tid & 63, tg = tid >> 6;
;     const int ch = c0 + c;
;     const float* cwp = p.in[4] + (size_t)l * 4 * 512;
;     const float cw0 = cwp[ch], cw1 = cwp[512 + ch], cw2 = cwp[1024 + ch], cw3 = cwp[1536 + ch];
;     const float cb = p.in[5][l * 512 + ch], ba = p.in[7][l * 512 + ch], bx = p.in[9][l * 512 + ch];
;     const float lam = p.in[10][l * 512 + ch];
;     const float logu = -8.0f * log1pf(expf(-lam));
;     const bf16* WaT = (const bf16*)wla_ptr(C.ws, l) + nb * 4096;
;     const bf16* WxT = (const bf16*)wlx_ptr(C.ws, l) + nb * 4096;
;     bf16x8 wa[4][2], wx[4][2];
; #pragma unroll
;     for (int nt = 0; nt < 4; ++nt)
; #pragma unroll
;         for (int ks = 0; ks < 2; ++ks) { wa[nt][ks] = *(const bf16x8*)(WaT + (16 * nt + i16) * 64 + 32 * ks + 8 * g); wx[nt][ks] = *(const bf16x8*)(WxT + (16 * nt + i16) * 64 + 32 * ks + 8 * g); }
;     if (tid < 64) { CAR[tid] = 0.f; CARP[tid] = 1.f; }
; __global__ void __launch_bounds__(512) hybrid_fwd(Params p) {
;     ...
;             if (C.tid == 0) s_unit = (int)atomicAdd(ctl + 64 * (1 + l), 1u);
;             __syncthreads();
;             const int u = s_unit;
;             __syncthreads();
;             if (u >= 1024 + 1024 + 512) break;
;             const int v2 = u - 512, grpq = v2 >> 7, rq = v2 & 127;
;     ...
;             if (u >= 512 && rq < 64) lru_unit(C, p, l, grpq * 64 + rq);
.LBB0_321:
	s_or_b64 exec, exec, s[40:41]
	s_waitcnt lgkmcnt(0)
	s_barrier
	ds_read_b32 v0, v193
	s_movk_i32 s19, 0x9ff
	s_mov_b64 s[40:41], -1
	s_waitcnt lgkmcnt(0)
	s_barrier
	v_cmp_lt_i32_e32 vcc, s19, v0
	v_readfirstlane_b32 s74, v0
	s_cbranch_vccnz .LBB0_316
	s_cmp_lt_u32 s74, 512
	s_cbranch_scc1 .Lq2_done
	s_sub_u32 s19, s74, 512
	s_lshr_b32 s20, s19, 8
	s_lshl_b32 s20, s20, 1
	s_bfe_u32 s21, s19, 0x10006
	s_add_u32 s20, s20, s21
	s_lshl_b32 s20, s20, 7
	s_and_b32 s21, s19, 63
	s_add_u32 s20, s20, s21
	s_bfe_u32 s21, s19, 0x10007
	s_lshl_b32 s21, s21, 6
	s_add_u32 s20, s20, s21
	s_add_u32 s74, s20, 512
.Lq2_done:
	s_add_i32 s19, s74, 0xfffffe00
	s_ashr_i32 s72, s73, 6
	s_ashr_i32 s19, s19, 7
	s_and_b32 s20, s74, 0x7f
	s_cmpk_gt_i32 s74, 0x1ff
	s_cselect_b64 s[6:7], -1, 0
	s_cmp_lt_u32 s20, 64
	s_cselect_b64 s[22:23], -1, 0
	v_and_b32_e32 v169, 63, v132
	s_and_b64 s[22:23], s[6:7], s[22:23]
	s_andn2_b64 vcc, exec, s[22:23]
	v_lshrrev_b32_e32 v186, 4, v169
	s_cbranch_vccnz .LBB0_381
	s_and_b32 s21, s74, 7
	s_lshl_b32 s56, s21, 6
	v_or_b32_e32 v114, s56, v169
	s_lshl_b32 s22, s20, 9
	v_lshlrev_b32_e32 v192, 2, v114
	v_readlane_b32 s0, v247, 13
	s_and_b32 s57, s22, 0x7000
	v_lshl_add_u64 v[0:1], s[60:61], 0, v[192:193]
	global_load_dword v115, v192, s[60:61]
	global_load_dword v116, v192, s[60:61] offset:2048
	v_or_b32_e32 v192, s0, v114
	v_readlane_b32 s0, v247, 10
	s_add_u32 s22, s64, s0
	s_addc_u32 s23, s65, 0
	s_lshl_b32 s21, s21, 13
	s_add_u32 s22, s22, s21
	v_add_co_u32_e32 v0, vcc, 0x1000, v0
	s_addc_u32 s23, s23, 0
	v_readlane_b32 s0, v247, 16
	v_addc_co_u32_e32 v1, vcc, 0, v1, vcc
	v_readlane_b32 s40, v249, 42
	s_add_u32 s24, s64, s0
	global_load_dword v117, v[0:1], off
	global_load_dword v118, v[0:1], off offset:2048
	v_lshlrev_b64 v[0:1], 2, v[192:193]
	v_readlane_b32 s50, v249, 52
	v_readlane_b32 s51, v249, 53
	s_addc_u32 s25, s65, 0
	v_readlane_b32 s41, v249, 43
	v_readlane_b32 s42, v249, 44
	v_readlane_b32 s43, v249, 45
	v_readlane_b32 s44, v249, 46
	v_readlane_b32 s45, v249, 47
	v_readlane_b32 s46, v249, 48
	v_readlane_b32 s47, v249, 49
	v_readlane_b32 s48, v249, 50
	v_readlane_b32 s49, v249, 51
	v_readlane_b32 s52, v249, 54
	v_readlane_b32 s53, v249, 55
	v_readlane_b32 s54, v249, 56
	v_readlane_b32 s55, v249, 57
	v_lshl_add_u64 v[2:3], s[50:51], 0, v[0:1]
	s_add_u32 s24, s24, s21
	v_and_b32_e32 v64, 15, v132
	global_load_dword v119, v[2:3], off
	v_lshl_add_u64 v[2:3], s[54:55], 0, v[0:1]
	v_readlane_b32 s40, v250, 10
	s_addc_u32 s25, s25, 0
	v_and_b32_e32 v192, 48, v169
	v_readlane_b32 s42, v250, 12
	v_readlane_b32 s43, v250, 13
	v_readlane_b32 s44, v250, 14
	v_readlane_b32 s45, v250, 15
	v_lshl_add_u64 v[48:49], s[22:23], 0, v[192:193]
	v_lshl_add_u64 v[50:51], s[24:25], 0, v[192:193]
	v_lshlrev_b32_e32 v192, 7, v64
	global_load_dword v120, v[2:3], off
	v_lshl_add_u64 v[2:3], s[42:43], 0, v[0:1]
	v_lshl_add_u64 v[0:1], s[44:45], 0, v[0:1]
	s_waitcnt vmcnt(12)
	v_lshl_add_u64 v[20:21], v[48:49], 0, v[192:193]
	s_waitcnt vmcnt(10)
	v_lshl_add_u64 v[28:29], v[50:51], 0, v[192:193]
	global_load_dword v121, v[2:3], off
	global_load_dword v65, v[0:1], off
	s_nop 0
	global_load_dwordx4 v[0:3], v[20:21], off
	global_load_dwordx4 v[4:7], v[20:21], off offset:64
	global_load_dwordx4 v[8:11], v[28:29], off
	global_load_dwordx4 v[12:15], v[28:29], off offset:64
	global_load_dwordx4 v[16:19], v[20:21], off offset:2048
	s_nop 0
	global_load_dwordx4 v[20:23], v[20:21], off offset:2112
	s_nop 0
	global_load_dwordx4 v[24:27], v[28:29], off offset:2048
	s_nop 0
	global_load_dwordx4 v[28:31], v[28:29], off offset:2112
	v_or_b32_e32 v32, 0x1000, v192
	v_mov_b32_e32 v33, v193
	v_or_b32_e32 v192, 0x1800, v192
	v_lshl_add_u64 v[36:37], v[48:49], 0, v[32:33]
	v_lshl_add_u64 v[44:45], v[50:51], 0, v[32:33]
	v_lshl_add_u64 v[52:53], v[48:49], 0, v[192:193]
	v_lshl_add_u64 v[60:61], v[50:51], 0, v[192:193]
	global_load_dwordx4 v[32:35], v[36:37], off
	s_nop 0
	global_load_dwordx4 v[36:39], v[36:37], off offset:64
	s_nop 0
	global_load_dwordx4 v[40:43], v[44:45], off
	s_nop 0
	global_load_dwordx4 v[44:47], v[44:45], off offset:64
	s_nop 0
	global_load_dwordx4 v[48:51], v[52:53], off
	s_nop 0
	global_load_dwordx4 v[52:55], v[52:53], off offset:64
	s_nop 0
	global_load_dwordx4 v[56:59], v[60:61], off
	s_nop 0
	global_load_dwordx4 v[60:63], v[60:61], off offset:64
	v_readlane_b32 s41, v250, 11
	v_cmp_gt_i32_e64 s[40:41], 64, v132
	v_readlane_b32 s46, v250, 16
	v_readlane_b32 s47, v250, 17
	v_readlane_b32 s48, v250, 18
	v_readlane_b32 s49, v250, 19
	v_readlane_b32 s50, v250, 20
	v_readlane_b32 s51, v250, 21
	v_readlane_b32 s52, v250, 22
	v_readlane_b32 s53, v250, 23
	v_readlane_b32 s54, v250, 24
	v_readlane_b32 s55, v250, 25
	s_and_saveexec_b64 s[42:43], s[40:41]
	s_cbranch_execz .LBB0_325
	v_lshl_add_u32 v66, v132, 2, 0
	v_add_u32_e32 v67, 0x15840, v66
	v_add_u32_e32 v66, 0x15940, v66
	ds_write_b32 v67, v193
	ds_write_b32 v66, v232
